# MLA (phase 14) and dilated-attention (phase 12) bodies deduplicated: layer 1 branches into layer 0 code with a return selector; no other change
# speedup vs baseline: 1.0010x; 1.0010x over previous
.Ldil_body:
	s_cmpk_gt_i32 s12, 0x13ff
	s_cbranch_scc1 .LBB0_211
	s_add_u32 s88, s70, 0x77a0000
	s_addc_u32 s89, s71, 0
	v_and_b32_e32 v0, 0x3fffffc0, v16
	s_add_i32 s0, 0, 0x18000
	v_ashrrev_i32_e32 v113, 3, v16
	v_lshl_add_u32 v1, v0, 2, s0
	v_lshlrev_b32_e32 v0, 1, v14
	v_and_b32_e32 v3, 32, v0
	v_lshlrev_b32_e32 v0, 4, v14
	v_lshlrev_b32_e32 v5, 3, v16
	v_lshrrev_b32_e32 v2, 1, v113
	v_and_b32_e32 v8, 3, v113
	v_and_b32_e32 v4, 0xc0, v0
	v_and_b32_e32 v0, 56, v5
	v_and_or_b32 v2, v2, 4, v8
	v_lshlrev_b32_e32 v6, 1, v0
	v_lshlrev_b32_e32 v8, 6, v2
	v_lshlrev_b32_e32 v2, 1, v113
	v_and_b32_e32 v9, 0x1fffff0, v113
	s_movk_i32 s0, 0x70
	v_and_or_b32 v2, v2, 8, v9
	v_bitop3_b32 v10, v6, v16, s0 bitop3:0x78
	s_add_i32 s0, 0, 0x18800
	v_lshrrev_b32_e32 v2, 2, v2
	v_bfe_u32 v9, v5, 5, 1
	v_lshl_add_u32 v11, v18, 12, s0
	s_movk_i32 s0, 0x118
	v_or_b32_e32 v9, v2, v9
	v_and_or_b32 v3, v17, s0, v3
	s_add_i32 s0, 0, 0xc000
	v_and_b32_e32 v7, 48, v6
	v_bfe_u32 v12, v14, 5, 1
	v_lshl_add_u32 v9, v9, 9, 0
	s_cmp_lg_u32 s0, -1
	v_and_b32_e32 v112, 31, v14
	v_add3_u32 v115, v9, v8, v7
	v_lshlrev_b32_e32 v7, 2, v12
	v_lshlrev_b32_e32 v8, 4, v12
	s_cselect_b32 s0, s0, 0
	v_cvt_f32_ubyte0_e32 v117, v7
	v_ashrrev_i32_e32 v7, 7, v16
	v_and_b32_e32 v5, 0x70, v5
	v_lshl_add_u32 v9, v112, 7, 0
	v_add3_u32 v3, v4, s0, v3
	v_cmp_gt_u32_e64 s[0:1], 32, v15
	v_or_b32_e32 v15, 32, v8
	v_lshl_add_u32 v4, v112, 1, v11
	v_bfe_u32 v119, v14, 3, 3
	v_add_u32_e32 v6, v11, v6
	v_add_u32_e32 v11, 1, v7
	v_add_u32_e32 v14, 2, v7
	v_xad_u32 v124, v15, v5, v9
	v_or_b32_e32 v15, 64, v8
	s_add_u32 s90, s70, 0x137a0000
	v_lshlrev_b32_e32 v120, 13, v7
	v_lshlrev_b32_e32 v122, 13, v11
	v_lshlrev_b32_e32 v123, 13, v14
	v_xad_u32 v125, v15, v5, v9
	v_or_b32_e32 v15, 0x60, v8
	v_or_b32_e32 v134, 8, v119
	v_or_b32_e32 v135, 16, v119
	v_or_b32_e32 v136, 24, v119
	s_addc_u32 s91, s71, 0
	v_mov_b32_e32 v109, 0
	v_lshlrev_b32_e32 v2, 3, v12
	v_lshl_add_u32 v13, v113, 7, 0
	v_lshl_add_u32 v118, v112, 2, v1
	v_xad_u32 v121, v8, v5, v9
	v_xad_u32 v126, v15, v5, v9
	v_lshlrev_b32_e32 v127, 6, v7
	v_add_u32_e32 v130, v3, v120
	v_add_u32_e32 v131, v3, v122
	v_add_u32_e32 v132, v3, v123
	v_add_u32_e32 v133, v1, v8
	v_lshlrev_b32_e32 v1, 9, v12
	v_lshlrev_b32_e32 v3, 7, v119
	v_lshlrev_b32_e32 v5, 7, v134
	v_lshlrev_b32_e32 v7, 7, v135
	v_lshlrev_b32_e32 v8, 7, v136
	s_add_u32 s92, s70, 0x1eea0000
	s_mov_b32 s10, 0x42000000
	s_mov_b32 s52, 2.0
	s_mov_b32 s54, 0x42080000
	s_mov_b32 s56, 0x41000000
	s_mov_b32 s58, 0x42200000
	s_mov_b32 s60, 0x41200000
	s_mov_b32 s62, 0x42280000
	s_mov_b32 s64, 0x41800000
	s_mov_b32 s66, 0x42400000
	s_mov_b32 s72, 0x41900000
	s_mov_b32 s74, 0x42480000
	s_mov_b32 s76, 0x41c00000
	s_mov_b32 s78, 0x42600000
	s_mov_b32 s80, 0x41d00000
	s_mov_b32 s82, 0x42680000
	s_mov_b32 s24, s84
	s_mov_b32 s9, 0
	v_lshlrev_b32_e32 v114, 5, v18
	v_add_u32_e32 v116, 0xc000, v115
	v_lshlrev_b32_e32 v128, 6, v11
	v_lshlrev_b32_e32 v129, 6, v14
	s_addc_u32 s93, s71, 0
	v_lshlrev_b32_e32 v108, 1, v0
	v_lshlrev_b32_e32 v110, 1, v2
	v_mov_b32_e32 v111, v109
	v_add_u32_e32 v137, v13, v10
	s_mov_b32 s11, 0x42040000
	s_mov_b32 s94, 0x42800000
	s_mov_b32 s95, 0xff61b1e6
	s_mov_b32 s53, 0x40400000
	s_mov_b32 s55, 0x420c0000
	s_mov_b32 s57, 0x41100000
	s_mov_b32 s59, 0x42240000
	s_mov_b32 s61, 0x41300000
	s_mov_b32 s63, 0x422c0000
	s_mov_b32 s65, 0x41880000
	s_mov_b32 s67, 0x42440000
	s_mov_b32 s73, 0x41980000
	s_mov_b32 s75, 0x424c0000
	s_mov_b32 s77, 0x41c80000
	s_mov_b32 s79, 0x42640000
	s_mov_b32 s81, 0x41d80000
	s_mov_b32 s83, 0x426c0000
	v_add_u32_e32 v138, v4, v1
	v_add_u32_e32 v139, v6, v3
	v_add_u32_e32 v140, v6, v5
	v_add_u32_e32 v141, v6, v7
	v_add_u32_e32 v142, v6, v8
	v_mov_b32_e32 v143, 0xf149f2ca
	s_mov_b32 s96, s12
	s_branch .LBB0_178

	.amdhsa_kernel _Z14fwd_megakernel6Params
		.amdhsa_group_segment_fixed_size 0
		.amdhsa_private_segment_fixed_size 0
		.amdhsa_kernarg_size 408
		.amdhsa_user_sgpr_count 2
		.amdhsa_user_sgpr_dispatch_ptr 0
		.amdhsa_user_sgpr_queue_ptr 0
		.amdhsa_user_sgpr_kernarg_segment_ptr 1
		.amdhsa_user_sgpr_dispatch_id 0
		.amdhsa_user_sgpr_kernarg_preload_length 0
		.amdhsa_user_sgpr_kernarg_preload_offset 0
		.amdhsa_user_sgpr_private_segment_size 0
		.amdhsa_uses_dynamic_stack 0
		.amdhsa_enable_private_segment 0
		.amdhsa_system_sgpr_workgroup_id_x 1
		.amdhsa_system_sgpr_workgroup_id_y 0
		.amdhsa_system_sgpr_workgroup_id_z 0
		.amdhsa_system_sgpr_workgroup_info 0
		.amdhsa_system_vgpr_workitem_id 2
		.amdhsa_next_free_vgpr 245
		.amdhsa_next_free_sgpr 102
		.amdhsa_accum_offset 248
		.amdhsa_reserve_vcc 1
		.amdhsa_float_round_mode_32 0
		.amdhsa_float_round_mode_16_64 0
		.amdhsa_float_denorm_mode_32 3
		.amdhsa_float_denorm_mode_16_64 3
		.amdhsa_dx10_clamp 1
		.amdhsa_ieee_mode 1
		.amdhsa_fp16_overflow 0
		.amdhsa_tg_split 0
		.amdhsa_exception_fp_ieee_invalid_op 0
		.amdhsa_exception_fp_denorm_src 0
		.amdhsa_exception_fp_ieee_div_zero 0
		.amdhsa_exception_fp_ieee_overflow 0
		.amdhsa_exception_fp_ieee_underflow 0
		.amdhsa_exception_fp_ieee_inexact 0
		.amdhsa_exception_int_div_zero 0
	.end_amdhsa_kernel

amdhsa.kernels:
  - .agpr_count:     0
    .args:
      - .offset:         0
        .size:           152
        .value_kind:     by_value
      - .offset:         152
        .size:           4
        .value_kind:     hidden_block_count_x
      - .offset:         156
        .size:           4
        .value_kind:     hidden_block_count_y
      - .offset:         160
        .size:           4
        .value_kind:     hidden_block_count_z
      - .offset:         164
        .size:           2
        .value_kind:     hidden_group_size_x
      - .offset:         166
        .size:           2
        .value_kind:     hidden_group_size_y
      - .offset:         168
        .size:           2
        .value_kind:     hidden_group_size_z
      - .offset:         170
        .size:           2
        .value_kind:     hidden_remainder_x
      - .offset:         172
        .size:           2
        .value_kind:     hidden_remainder_y
      - .offset:         174
        .size:           2
        .value_kind:     hidden_remainder_z
      - .offset:         192
        .size:           8
        .value_kind:     hidden_global_offset_x
      - .offset:         200
        .size:           8
        .value_kind:     hidden_global_offset_y
      - .offset:         208
        .size:           8
        .value_kind:     hidden_global_offset_z
      - .offset:         216
        .size:           2
        .value_kind:     hidden_grid_dims
      - .offset:         240
        .size:           8
        .value_kind:     hidden_multigrid_sync_arg
      - .offset:         272
        .size:           4
        .value_kind:     hidden_dynamic_lds_size
    .group_segment_fixed_size: 0
    .kernarg_segment_align: 8
    .kernarg_segment_size: 408
    .language:       OpenCL C
    .language_version:
      - 2
      - 0
    .max_flat_workgroup_size: 512
    .name:           _Z14fwd_megakernel6Params
    .private_segment_fixed_size: 0
    .sgpr_count:     108
    .sgpr_spill_count: 16
    .symbol:         _Z14fwd_megakernel6Params.kd
    .uniform_work_group_size: 1
    .uses_dynamic_stack: false
    .vgpr_count:     245
    .vgpr_spill_count: 0
    .wavefront_size: 64
